# mixer B exact early exit at the bf16 zero bound (134.1 instead of 150.1), on top of the de-serialised epilogues
# speedup vs baseline: 1.6407x; 1.0042x over previous
; #define LAS __attribute__((address_space(3)))
; #define MFMA32(a, b, c) __builtin_amdgcn_mfma_f32_32x32x16_bf16((a), (b), (c), 0, 0, 0)
; DI void attnB_item(bf16_t* z, int hh, int qs, LAS bf16_t* vs, int lane) {
;     ...
;         for (int i = 0; i < 8; ++i) *(LAS u32x4*)(vs + (16 * (i >> 2) + (lane & 15)) * PB + 32 * (i & 3) + 8 * (lane >> 4)) = vv[i];
; #pragma unroll
;         for (int i = 0; i < 8; ++i) vv[i] = *(const u32x4*)(vbase + ron + (((i >> 2) << 13) | ((i & 3) << 9)));
;         asm volatile("" ::: "memory");
;         bf16x8 af[2][4];
; #pragma unroll
;         for (int s = 0; s < 2; ++s)
; #pragma unroll
;             for (int dt = 0; dt < 4; ++dt) { const LAS bf16_t* lo = vs + trb + 16 * s * PB + 32 * dt; af[s][dt] = tr_frag(lo, lo + 8 * PB); }
;         asm volatile("s_waitcnt lgkmcnt(0)" ::: "memory"); __builtin_amdgcn_sched_barrier(0);
;         __builtin_amdgcn_s_setprio(1);
; #pragma unroll
;         for (int s = 0; s < 2; ++s) {
;             const u32x4 pwv = {pw[4 * s], pw[4 * s + 1], pw[4 * s + 2], pw[4 * s + 3]};
;             const bf16x8 bfrag = __builtin_bit_cast(bf16x8, pwv);
; #pragma unroll
;             for (int dt = 0; dt < 4; ++dt) acc[dt] = MFMA32(af[s][dt], bfrag, acc[dt]);
;         }
;         __builtin_amdgcn_s_setprio(0);
;         if (t < 0) break;
;         if (__all(later > 150.1f)) break;
.LBB0_155:
	s_waitcnt vmcnt(15)
	ds_write_b128 v188, v[82:85]
	s_waitcnt vmcnt(14)
	ds_write_b128 v188, v[86:89] offset:64
	s_waitcnt vmcnt(13)
	ds_write_b128 v188, v[90:93] offset:128
	s_waitcnt vmcnt(12)
	ds_write_b128 v188, v[94:97] offset:192
	s_waitcnt vmcnt(11)
	ds_write_b128 v188, v[98:101] offset:5120
	s_waitcnt vmcnt(10)
	ds_write_b128 v188, v[102:105] offset:5184
	s_waitcnt vmcnt(9)
	ds_write_b128 v188, v[106:109] offset:5248
	s_waitcnt vmcnt(8)
	ds_write_b128 v188, v[110:113] offset:5312
	v_lshl_add_u64 v[66:67], s[6:7], 1, v[160:161]
	global_load_dwordx4 v[82:85], v[66:67], off
	global_load_dwordx4 v[86:89], v[66:67], off offset:1024
	global_load_dwordx4 v[90:93], v[66:67], off offset:2048
	global_load_dwordx4 v[94:97], v[66:67], off offset:3072
	v_add_co_u32_e32 v66, vcc, s3, v66
	s_nop 1
	v_addc_co_u32_e32 v67, vcc, 0, v67, vcc
	global_load_dwordx4 v[98:101], v[66:67], off
	global_load_dwordx4 v[102:105], v[66:67], off offset:1024
	global_load_dwordx4 v[106:109], v[66:67], off offset:2048
	global_load_dwordx4 v[110:113], v[66:67], off offset:3072
	ds_read_b64_tr_b16 v[66:67], v190
	ds_read_b64_tr_b16 v[70:71], v190 offset:64
	ds_read_b64_tr_b16 v[74:75], v190 offset:128
	ds_read_b64_tr_b16 v[78:79], v190 offset:192
	ds_read_b64_tr_b16 v[68:69], v190 offset:2560
	ds_read_b64_tr_b16 v[72:73], v190 offset:2624
	ds_read_b64_tr_b16 v[76:77], v190 offset:2688
	ds_read_b64_tr_b16 v[80:81], v190 offset:2752
	ds_read_b64_tr_b16 v[192:193], v190 offset:5120
	ds_read_b64_tr_b16 v[196:197], v190 offset:5184
	ds_read_b64_tr_b16 v[200:201], v190 offset:5248
	ds_read_b64_tr_b16 v[204:205], v190 offset:5312
	ds_read_b64_tr_b16 v[194:195], v190 offset:7680
	ds_read_b64_tr_b16 v[198:199], v190 offset:7744
	ds_read_b64_tr_b16 v[202:203], v190 offset:7808
	ds_read_b64_tr_b16 v[206:207], v190 offset:7872
	s_waitcnt lgkmcnt(0)
	s_setprio 1
	s_waitcnt lgkmcnt(11)
	v_mfma_f32_32x32x16_bf16 v[50:65], v[66:69], v[146:149], v[50:65]
	s_waitcnt lgkmcnt(10)
	v_mfma_f32_32x32x16_bf16 v[34:49], v[70:73], v[146:149], v[34:49]
	s_waitcnt lgkmcnt(9)
	v_mfma_f32_32x32x16_bf16 v[18:33], v[74:77], v[146:149], v[18:33]
	s_waitcnt lgkmcnt(8)
	v_mfma_f32_32x32x16_bf16 v[2:17], v[78:81], v[146:149], v[2:17]
	s_waitcnt lgkmcnt(3)
	v_mfma_f32_32x32x16_bf16 v[50:65], v[192:195], v[150:153], v[50:65]
	s_waitcnt lgkmcnt(2)
	v_mfma_f32_32x32x16_bf16 v[34:49], v[196:199], v[150:153], v[34:49]
	s_waitcnt lgkmcnt(1)
	v_mfma_f32_32x32x16_bf16 v[18:33], v[200:203], v[150:153], v[18:33]
	s_waitcnt lgkmcnt(0)
	v_mfma_f32_32x32x16_bf16 v[2:17], v[204:207], v[150:153], v[2:17]
	s_setprio 0
	s_andn2_b64 vcc, exec, s[4:5]
	s_mov_b64 s[4:5], -1
	s_cbranch_vccnz .LBB0_150
	v_add_f32_e32 v189, v189, v208
	s_mov_b32 s4, 0x4306199a
	v_cmp_lt_f32_e32 vcc, s4, v189
	s_cmp_eq_u64 vcc, exec
	s_cselect_b64 s[4:5], -1, 0
	s_branch .LBB0_150
